# GLA chunk staging by LDS-DMA (q/k after the stage-1 barrier, v after the stage-2 barrier) instead of VGPR staging + ds_write_b128
# speedup vs baseline: 1.0010x; 1.0007x over previous
; #define LAS __attribute__((address_space(3)))
; __device__ __forceinline__ unsigned cvtpk(float lo, float hi) { f32x2 v = {lo, hi}; bf16x2_t b = __builtin_convertvector(v, bf16x2_t); return __builtin_bit_cast(unsigned, b); }
; __device__ __forceinline__ void gla_unit(LAS char* lds0, int b, int h, int dvh, bf16_t* Z, bf16_t* OT, const float* afw, const float* afb, const float* abw, const float* abb, bool dry) {
;     int tid = threadIdx.x; asm volatile("" : "+v"(tid)); const int lane = tid & 63, r32 = lane & 31, hi = lane >> 5; const int wid = __builtin_amdgcn_readfirstlane(tid >> 6);
;     const int dir = wid >> 2, wg = wid & 3, tg = tid & 255;
;     LAS char* lds = lds0 + dir * G_GROUP;
;     const int g16 = (lane >> 4) & 1, q4 = (lane & 15) >> 2, p4 = lane & 3;
;     const int I = wg >> 1, J = wg & 1;
;     const float* w2 = dir ? abw : afw; const float* bb = dir ? abb : afb;
;     bf16x8 w2b;
;     { u32x4 t; t.x = cvtpk(w2[(8 * hi + 0) * 256 + h * 64 + 32 * J + r32], w2[(8 * hi + 1) * 256 + h * 64 + 32 * J + r32]);
;       t.y = cvtpk(w2[(8 * hi + 2) * 256 + h * 64 + 32 * J + r32], w2[(8 * hi + 3) * 256 + h * 64 + 32 * J + r32]);
;       t.z = cvtpk(w2[(8 * hi + 4) * 256 + h * 64 + 32 * J + r32], w2[(8 * hi + 5) * 256 + h * 64 + 32 * J + r32]);
;       t.w = cvtpk(w2[(8 * hi + 6) * 256 + h * 64 + 32 * J + r32], w2[(8 * hi + 7) * 256 + h * 64 + 32 * J + r32]);
;       w2b = __builtin_bit_cast(bf16x8, t); }
;     const float bias = bb[h * 64 + 32 * J + r32];
;     const int zcol_a = dir ? ZAB : ZAF;
;     f32x16 S = {};
;     for (int i = tg; i < GARR / 4; i += 256) ((LAS unsigned*)(lds + G_SB))[i] = 0u;
;     u32x4 pq0, pq1, pk0, pk1, pv0, pv1; u32x2 pa;
;     const int lr = tg >> 3, lc = tg & 7, ar = tg >> 2, ac = tg & 3;
;     ...
;     GLA_PREFETCH(0);
.LBB0_401:
	v_mov_b32_e32 v6, v182
	s_bfe_u32 s8, s97, 0x20001
	v_readfirstlane_b32 s28, v6
	s_lshr_b32 s0, s28, 8
	s_mul_i32 s0, s0, 0x10a00
	s_add_i32 s76, s0, 0
	s_bfe_u32 s42, s28, 0x10006
	s_cmpk_lt_u32 s28, 0x100
	s_cselect_b64 s[0:1], -1, 0
	s_cmpk_gt_u32 s28, 0xff
	v_readlane_b32 s52, v254, 59
	s_cselect_b64 s[16:17], -1, 0
	s_and_b64 s[2:3], s[0:1], exec
	v_readlane_b32 s54, v254, 61
	v_readlane_b32 s58, v255, 1
	v_readlane_b32 s55, v254, 62
	v_readlane_b32 s59, v255, 2
	s_cselect_b32 s2, s54, s58
	s_cselect_b32 s3, s55, s59
	s_add_u32 s2, s2, s94
	s_addc_u32 s3, s3, s95
	v_readlane_b32 s56, v254, 63
	s_and_b64 s[14:15], s[0:1], exec
	v_readlane_b32 s44, v254, 55
	v_readlane_b32 s57, v255, 0
	v_readlane_b32 s45, v254, 56
	s_cselect_b32 s15, s56, s44
	v_readlane_b32 s24, v255, 36
	v_bfe_u32 v16, v6, 3, 5
	s_cselect_b32 s14, s57, s45
	v_readlane_b32 s25, v255, 37
	s_add_u32 s24, s15, s24
	v_and_b32_e32 v14, 31, v6
	v_bfe_u32 v15, v6, 5, 1
	v_xor_b32_e32 v0, 63, v16
	s_addc_u32 s25, s14, s25
	s_lshl_b32 s43, s42, 5
	v_cndmask_b32_e64 v114, v0, v16, s[0:1]
	v_lshlrev_b32_e32 v0, 11, v15
	s_lshl_b32 s77, s8, 6
	v_or_b32_e32 v18, s43, v14
	v_or3_b32 v0, v0, s77, v18
	v_lshlrev_b32_e32 v0, 2, v0
	v_lshl_add_u64 v[2:3], s[2:3], 0, v[0:1]
	global_load_dword v17, v0, s[2:3]
	global_load_dword v19, v0, s[2:3] offset:1024
	global_load_dword v21, v0, s[2:3] offset:2048
	s_nop 0
	global_load_dword v0, v0, s[2:3] offset:3072
	s_movk_i32 s2, 0x1000
	v_add_co_u32_e32 v2, vcc, s2, v2
	s_ashr_i32 s2, s97, 3
	s_nop 0
	v_addc_co_u32_e32 v3, vcc, 0, v3, vcc
	s_lshr_b32 s40, s28, 7
	s_bfe_u32 s84, s28, 0x10007
	global_load_dword v22, v[2:3], off
	global_load_dword v23, v[2:3], off offset:1024
	global_load_dword v24, v[2:3], off offset:2048
	s_nop 0
	global_load_dword v3, v[2:3], off offset:3072
	v_and_b32_e32 v2, 0xff, v6
	s_and_b64 s[14:15], s[0:1], exec
	v_lshrrev_b32_e32 v25, 5, v6
	v_bfe_u32 v26, v6, 2, 2
	v_and_b32_e32 v27, 16, v6
	v_and_b32_e32 v28, 3, v6
	v_and_b32_e32 v7, 7, v6
	v_bfe_u32 v29, v6, 2, 6
	v_xor_b32_e32 v6, 31, v16
	v_or_b32_e32 v8, 32, v16
	v_lshl_add_u32 v2, v2, 2, s76
	s_mul_hi_i32 s14, s2, 0x900
	s_mul_i32 s15, s2, 0x900
	s_movk_i32 s2, 0x380
	s_cselect_b32 s34, 0, 0xc0
	ds_write2st64_b32 v2, v1, v1 offset0:180 offset1:184
	ds_write2st64_b32 v2, v1, v1 offset0:188 offset1:192
	ds_write2st64_b32 v2, v1, v1 offset0:196 offset1:200
	ds_write2st64_b32 v2, v1, v1 offset0:204 offset1:208
	ds_write_b32 v2, v1 offset:54272
	v_cndmask_b32_e64 v118, v6, v8, s[0:1]
	v_or_b32_e32 v2, s77, v18
	s_cselect_b32 s28, s2, 0x3a0
	s_or_b32 s34, s34, s15
	v_mov_b64_e32 v[4:5], s[88:89]
	v_lshlrev_b32_e32 v2, 2, v2
	v_or_b32_e32 v6, s34, v114
	v_or_b32_e32 v8, s34, v118
	v_lshlrev_b32_e32 v20, 3, v7
	v_lshlrev_b32_e32 v116, 4, v7
	global_load_dword v2, v2, s[24:25]
	v_mad_u64_u32 v[6:7], s[24:25], v6, s13, v[4:5]
	v_mad_u64_u32 v[8:9], s[24:25], v8, s13, v[4:5]
	s_mov_b32 s3, s9
	s_lshl_b32 s2, s8, 7
	v_mad_i32_i24 v7, s14, v204, v7
	v_mad_i32_i24 v9, s14, v204, v9
	v_lshl_add_u64 v[10:11], v[6:7], 0, s[2:3]
	v_lshl_add_u64 v[12:13], v[8:9], 0, s[2:3]
	s_lshl_b32 s3, s97, 6
	s_lshl_b32 s8, s8, 8
	s_and_b32 s3, s3, 64
	s_mov_b32 s29, 0
	v_lshl_add_u64 v[6:7], v[6:7], 0, s[8:9]
	s_lshl_b32 s24, s3, 1
	s_mov_b32 s25, s9
	v_mov_b32_e32 v117, v1
	v_lshl_add_u64 v[6:7], v[6:7], 0, s[24:25]
	v_lshl_add_u64 v[8:9], v[8:9], 0, s[8:9]
	v_lshl_add_u64 v[10:11], v[10:11], 0, v[116:117]
	v_lshl_add_u64 v[12:13], v[12:13], 0, v[116:117]
	v_lshl_add_u64 v[6:7], v[6:7], 0, v[116:117]
	v_lshl_add_u64 v[8:9], v[8:9], 0, s[24:25]
	global_load_dwordx4 v[70:73], v[10:11], off offset:2048
	global_load_dwordx4 v[74:77], v[10:11], off offset:2560
	global_load_dwordx4 v[78:81], v[12:13], off offset:2048
	global_load_dwordx4 v[82:85], v[12:13], off offset:2560
	v_lshl_add_u64 v[8:9], v[8:9], 0, v[116:117]
	global_load_dwordx4 v[86:89], v[6:7], off offset:3072
	global_load_dwordx4 v[90:93], v[8:9], off offset:3072
	v_and_b32_e32 v6, 64, v203
	v_add_u32_e32 v6, 64, v6
	v_lshlrev_b32_e32 v30, 3, v15
	v_mov_b32_e32 v31, s76
	s_movk_i32 s44, 0x90
	v_mad_u32_u24 v136, v18, s44, v31
	v_or_b32_e32 v44, v30, v26
	v_readlane_b32 s46, v254, 57
	v_readlane_b32 s47, v254, 58
	v_mul_u32_u24_e32 v154, 0x90, v44
	v_or_b32_e32 v44, 16, v30
	v_or_b32_e32 v46, 32, v30
	v_or_b32_e32 v30, 48, v30
	v_readlane_b32 s53, v254, 60
	v_mad_u32_u24 v115, v16, s44, v31
	s_or_b32 s18, s84, s42
	v_and_b32_e32 v244, 0xff, v182
	v_lshl_add_u32 v241, v244, 4, v31
	v_mov_b32_e32 v198, 0x200
	v_mov_b32_e32 v199, 0
	v_mov_b32_e32 v247, v244
	v_mul_u32_u24_e32 v245, 0x1c72, v247
	v_lshrrev_b32_e32 v245, 16, v245
	v_mul_u32_u24_e32 v246, 9, v245
	v_sub_u32_e32 v246, v247, v246
	v_cmp_eq_u32_e32 vcc, 8, v246
	v_cndmask_b32_e64 v246, v246, 0, vcc
	v_lshlrev_b32_e32 v246, 4, v246
	v_add_u32_e32 v200, 0x800, v246
	v_mov_b32_e32 v201, 0
	v_add_u32_e32 v192, 0xc00, v246
	v_mov_b32_e32 v193, 0
	v_xor_b32_e32 v246, 63, v245
	v_cndmask_b32_e64 v184, v246, v245, s[0:1]
	v_add_u32_e32 v247, 0x100, v244
	v_mul_u32_u24_e32 v245, 0x1c72, v247
	v_lshrrev_b32_e32 v245, 16, v245
	v_mul_u32_u24_e32 v246, 9, v245
	v_sub_u32_e32 v246, v247, v246
	v_cmp_eq_u32_e32 vcc, 8, v246
	v_cndmask_b32_e64 v246, v246, 0, vcc
	v_lshlrev_b32_e32 v246, 4, v246
	v_add_u32_e32 v248, 0x800, v246
	v_mov_b32_e32 v249, 0
	v_add_u32_e32 v194, 0xc00, v246
	v_mov_b32_e32 v195, 0
	v_xor_b32_e32 v246, 63, v245
	v_cndmask_b32_e64 v185, v246, v245, s[0:1]
	v_add_u32_e32 v247, 0x200, v244
	v_mul_u32_u24_e32 v245, 0x1c72, v247
	v_lshrrev_b32_e32 v245, 16, v245
	v_mul_u32_u24_e32 v246, 9, v245
	v_sub_u32_e32 v246, v247, v246
	v_cmp_eq_u32_e32 vcc, 8, v246
	v_cndmask_b32_e64 v246, v246, 0, vcc
	v_lshlrev_b32_e32 v246, 4, v246
	v_add_u32_e32 v250, 0x800, v246
	v_mov_b32_e32 v251, 0
	v_add_u32_e32 v196, 0xc00, v246
	v_mov_b32_e32 v197, 0
	v_xor_b32_e32 v246, 63, v245
	v_cndmask_b32_e64 v205, v246, v245, s[0:1]
	s_waitcnt vmcnt(0)
; __device__ __forceinline__ void gla_unit(LAS char* lds0, int b, int h, int dvh, bf16_t* Z, bf16_t* OT, const float* afw, const float* afb, const float* abw, const float* abb, bool dry) {
;     ...
;     f32x16 S = {};
;     for (int i = tg; i < GARR / 4; i += 256) ((LAS unsigned*)(lds + G_SB))[i] = 0u;
;     u32x4 pq0, pq1, pk0, pk1, pv0, pv1; u32x2 pa;
;     const int lr = tg >> 3, lc = tg & 7, ar = tg >> 2, ac = tg & 3;
;     ...
;     GLA_PREFETCH(0);
;     for (int s = 0; s < 36; ++s) {
;         const int c = GLA_CHUNK(s);
;         const size_t rbase = (size_t)b * TOK + 64 * c;
;         const int other_step = dir ? c : (c < 4 ? 3 - c : 39 - c);
;         const bool second = s > other_step;
;         *(LAS u32x4*)(lds + G_Q + lr * GP + lc * 16) = pq0; *(LAS u32x4*)(lds + G_Q + (lr + 32) * GP + lc * 16) = pq1;
;         *(LAS u32x4*)(lds + G_K + lr * GP + lc * 16) = pk0; *(LAS u32x4*)(lds + G_K + (lr + 32) * GP + lc * 16) = pk1;
;         *(LAS u32x4*)(lds + G_V + lr * GP + lc * 16) = pv0; *(LAS u32x4*)(lds + G_V + (lr + 32) * GP + lc * 16) = pv1;
;         *(LAS u32x2*)(lds + G_A16 + ar * 32 + ac * 8) = pa;
;         __syncthreads();
;         if (s + 1 < 36) GLA_PREFETCH(s + 1);
;         u32x4 prv0 = {0u, 0u, 0u, 0u}, prv1 = {0u, 0u, 0u, 0u};
;         bf16_t* og0 = OT + GLA_ROW(rbase, lr) * 512 + h * 128 + dvh * 64 + lc * 8;
;         bf16_t* og1 = OT + GLA_ROW(rbase, lr + 32) * 512 + h * 128 + dvh * 64 + lc * 8;
;         if (second) { prv0 = *(const u32x4*)og0; prv1 = *(const u32x4*)og1; }
;         float cs[16];
;         {
;             f32x16 zc;
; #pragma unroll
;             for (int r = 0; r < 16; ++r) zc[r] = bias;
;             const bf16x8 a = *(const LAS bf16x8*)(lds + G_A16 + (32 * I + r32) * 32 + hi * 16);
;             zc = __builtin_amdgcn_mfma_f32_32x32x16_bf16(a, w2b, zc, 0, 0, 0);
; #pragma unroll
;             for (int r = 0; r < 16; ++r) { const float z = zc[r]; cs[r] = (fminf(z, 0.f) - __logf(1.f + fexp(-fabsf(z)))) * (1.f / 16.f); }
;         }
; #pragma unroll
;         for (int g = 0; g < 4; ++g) { cs[4 * g + 1] += cs[4 * g]; cs[4 * g + 2] += cs[4 * g + 1]; cs[4 * g + 3] += cs[4 * g + 2]; }
;         float run = 0.f;
; #pragma unroll
;         for (int g = 0; g < 4; ++g) {
;             const float mine = cs[4 * g + 3]; const float oth = __shfl_xor(mine, 32);
;             const float off = run + (hi ? oth : 0.f);
; #pragma unroll
	v_cvt_pk_bf16_f32 v67, v21, v0
	v_xor_b32_e32 v0, 63, v29
	v_cndmask_b32_e64 v120, v0, v29, s[0:1]
	v_or_b32_e32 v0, s34, v120
	v_mad_u64_u32 v[4:5], s[34:35], v0, s13, v[4:5]
	v_mad_i32_i24 v5, s14, v204, v5
	v_lshl_add_u64 v[4:5], v[4:5], 0, s[28:29]
	v_lshlrev_b32_e32 v0, 3, v28
	v_lshl_add_u64 v[4:5], v[4:5], 0, v[0:1]
	global_load_dwordx2 v[126:127], v[4:5], off
	s_add_u32 s34, s88, s28
	s_addc_u32 s35, s89, 0
	v_lshl_add_u64 v[122:123], s[34:35], 0, v[0:1]
	v_readlane_b32 s34, v252, 21
	v_readlane_b32 s35, v252, 22
	s_add_u32 s8, s34, s8
	s_addc_u32 s25, s35, 0
	s_add_u32 s24, s8, s24
	s_addc_u32 s25, s25, 0
	v_lshl_add_u64 v[124:125], s[24:25], 0, v[116:117]
	s_add_i32 s24, s76, 0x10500
	s_lshl_b32 s28, s42, 7
	v_xor_b32_e32 v5, 32, v203
	s_lshl_b32 s25, s84, 8
	s_add_i32 s28, s24, s28
	s_lshl_b32 s8, s84, 5
	v_cmp_lt_i32_e32 vcc, v5, v6
	s_add_i32 s25, s28, s25
	v_cvt_pk_bf16_f32 v68, v22, v23
	v_cndmask_b32_e32 v5, v203, v5, vcc
	v_lshlrev_b32_e32 v6, 2, v18
	s_cmp_eq_u32 s84, 0
	v_lshl_or_b32 v23, v15, 2, s8
	v_lshl_add_u32 v21, v29, 5, s76
	v_lshlrev_b32_e32 v119, 2, v5
	v_lshlrev_b32_e32 v5, 2, v14
	v_add_u32_e32 v132, s24, v6
	s_cselect_b64 s[34:35], -1, 0
	s_add_i32 s24, s76, 0x10400
	v_mul_u32_u24_e32 v29, 0x48, v23
	v_cvt_pk_bf16_f32 v69, v24, v3
	v_lshlrev_b32_e32 v3, 2, v28
	v_or_b32_e32 v4, s8, v14
	v_add_u32_e32 v121, s25, v5
	v_lshlrev_b32_e32 v24, 1, v18
	s_cmp_le_u32 s42, s84
	s_movk_i32 s25, 0xff72
	v_lshlrev_b32_e32 v29, 1, v29
	v_lshl_add_u32 v22, v4, 5, s76
	v_lshlrev_b32_e32 v117, 4, v15
	v_add_u32_e32 v133, s28, v5
	v_bitop3_b32 v5, s40, 1, v25 bitop3:0xc8
	s_cselect_b64 s[78:79], -1, 0
	v_mad_u32_u24 v135, v4, s44, v31
	v_or3_b32 v4, v3, v27, s43
	v_mad_i32_i24 v25, v18, s25, v136
	v_lshl_add_u32 v238, v23, 1, v136
	v_add_u32_e32 v239, v136, v117
	s_lshl_b32 s25, s42, 6
	v_or3_b32 v3, v27, s8, v3
	v_add3_u32 v138, s76, v24, v29
	v_or_b32_e32 v29, 2, v23
	s_add_i32 s8, s76, 0x10420
	v_lshl_add_u32 v137, v4, 1, s76
	s_add_i32 s25, s76, s25
	v_lshl_add_u32 v27, v3, 1, s76
	v_or_b32_e32 v24, 1, v23
	v_or_b32_e32 v31, 3, v23
	v_or_b32_e32 v32, 8, v23
	v_or_b32_e32 v33, 9, v23
	v_or_b32_e32 v34, 10, v23
	v_or_b32_e32 v35, 11, v23
	v_or_b32_e32 v36, 16, v23
	v_or_b32_e32 v37, 17, v23
	v_or_b32_e32 v38, 18, v23
	v_or_b32_e32 v39, 19, v23
	v_or_b32_e32 v40, 24, v23
	v_or_b32_e32 v41, 25, v23
	v_or_b32_e32 v42, 26, v23
	v_or_b32_e32 v43, 27, v23
	v_lshlrev_b32_e32 v45, 1, v44
	v_or_b32_e32 v44, v44, v26
	v_lshlrev_b32_e32 v47, 1, v46
	v_or_b32_e32 v46, v46, v26
	v_or_b32_e32 v26, v30, v26
	v_cmp_lt_u32_e64 s[46:47], v29, v18
	v_add_u32_e32 v29, s8, v117
	s_add_i32 s8, s76, 0x10440
	s_add_i32 s76, s76, 0x10460
	v_cvt_pk_bf16_f32 v66, v17, v19
	v_add_u32_e32 v19, 0x1200, v115
	v_lshl_add_u32 v28, v14, 1, s25
	v_mul_u32_u24_e32 v44, 0x90, v44
	v_mul_u32_u24_e32 v46, 0x90, v46
	v_lshlrev_b32_e32 v48, 1, v30
	v_mul_u32_u24_e32 v26, 0x90, v26
	v_cmp_lt_u32_e64 s[42:43], v23, v18
	v_mul_u32_u24_e32 v23, 0x90, v23
	v_cmp_lt_u32_e64 s[44:45], v24, v18
	v_cmp_lt_u32_e64 s[50:51], v31, v18
	v_cmp_lt_u32_e64 s[52:53], v32, v18
	v_cmp_lt_u32_e64 s[54:55], v33, v18
	v_cmp_lt_u32_e64 s[56:57], v34, v18
	v_cmp_lt_u32_e64 s[58:59], v35, v18
	v_cmp_lt_u32_e64 s[60:61], v36, v18
	v_cmp_lt_u32_e64 s[62:63], v37, v18
	v_cmp_lt_u32_e64 s[64:65], v38, v18
	v_cmp_lt_u32_e64 s[66:67], v39, v18
	v_cmp_lt_u32_e64 s[68:69], v40, v18
	v_cmp_lt_u32_e64 s[70:71], v41, v18
	v_cmp_lt_u32_e64 s[72:73], v42, v18
	v_cmp_lt_u32_e64 s[74:75], v43, v18
	s_lshl_b32 s25, s84, 7
	v_add_u32_e32 v24, s24, v117
	v_add_u32_e32 v30, s8, v117
	v_add_u32_e32 v31, s76, v117
	v_mov_b32_e32 v18, 0
	v_cmp_eq_u32_e64 s[38:39], 0, v15
	v_cmp_eq_u32_e64 s[40:41], 0, v5
	v_add_u32_e32 v134, s24, v6
	v_mov_b32_e32 v3, v2
	v_mov_b32_e32 v4, v2
	v_mov_b32_e32 v5, v2
	v_mov_b32_e32 v6, v2
	v_mov_b32_e32 v7, v2
	v_mov_b32_e32 v8, v2
	v_mov_b32_e32 v9, v2
	v_mov_b32_e32 v10, v2
	v_mov_b32_e32 v11, v2
	v_mov_b32_e32 v12, v2
	v_mov_b32_e32 v13, v2
	v_mov_b32_e32 v14, v2
	v_mov_b32_e32 v15, v2
	v_mov_b32_e32 v16, v2
	v_mov_b32_e32 v17, v2
	v_add_u32_e32 v139, 0x90, v138
	s_waitcnt lgkmcnt(5)
	v_add_u32_e32 v140, 0x120, v138
	v_add_u32_e32 v141, 0x1b0, v138
	v_add_u32_e32 v142, 0x480, v138
	v_add_u32_e32 v143, 0x510, v138
	v_add_u32_e32 v144, 0x5a0, v138
	v_add_u32_e32 v145, 0x630, v138
	v_add_u32_e32 v146, 0x900, v138
	v_add_u32_e32 v147, 0x990, v138
	v_add_u32_e32 v148, 0xa20, v138
	v_add_u32_e32 v149, 0xab0, v138
	v_add_u32_e32 v150, 0xd80, v138
	v_add_u32_e32 v151, 0xe10, v138
	v_add_u32_e32 v152, 0xea0, v138
	v_add_u32_e32 v153, 0xf30, v138
	v_add_u32_e32 v155, v21, v0
	s_lshl_b32 s8, s77, 1
	v_lshlrev_b32_e32 v0, 1, v20
	s_lshl_b32 s24, s2, 1
	s_lshl_b32 s84, s3, 1
	v_add_u32_e32 v156, v22, v117
	v_add_u32_e32 v157, v137, v44
	v_add_u32_e32 v158, v137, v46
	v_add_u32_e32 v159, v137, v26
	v_add_u32_e32 v160, v25, v23
	v_add_u32_e32 v161, v28, v23
	v_add_u32_e32 v162, s25, v24
	v_add_u32_e32 v163, s25, v29
	v_add_u32_e32 v164, s25, v30
	v_add_u32_e32 v165, s25, v31
	v_add_u32_e32 v166, v27, v154
	v_add_u32_e32 v167, v19, v116
	v_add_u32_e32 v168, v135, v45
	v_add_u32_e32 v169, v135, v47
	v_add_u32_e32 v170, v135, v48
	s_mov_b32 s76, s29
	v_mov_b32_e32 v19, v18
	v_mov_b32_e32 v20, v18
	v_mov_b32_e32 v21, v18
	v_mov_b32_e32 v22, v18
	v_mov_b32_e32 v23, v18
	v_mov_b32_e32 v24, v18
	v_mov_b32_e32 v25, v18
	v_mov_b32_e32 v26, v18
	v_mov_b32_e32 v27, v18
	v_mov_b32_e32 v28, v18
	v_mov_b32_e32 v29, v18
	v_mov_b32_e32 v30, v18
	v_mov_b32_e32 v31, v18
	v_mov_b32_e32 v32, v18
	v_mov_b32_e32 v33, v18
	s_branch .LBB0_403

; #define LAS __attribute__((address_space(3)))
; __device__ __forceinline__ void gla_unit(LAS char* lds0, int b, int h, int dvh, bf16_t* Z, bf16_t* OT, const float* afw, const float* afb, const float* abw, const float* abb, bool dry) {
;     ...
;         *(LAS u32x4*)(lds + G_Q + lr * GP + lc * 16) = pq0; *(LAS u32x4*)(lds + G_Q + (lr + 32) * GP + lc * 16) = pq1;
;         *(LAS u32x4*)(lds + G_K + lr * GP + lc * 16) = pk0; *(LAS u32x4*)(lds + G_K + (lr + 32) * GP + lc * 16) = pk1;
;         *(LAS u32x4*)(lds + G_V + lr * GP + lc * 16) = pv0; *(LAS u32x4*)(lds + G_V + (lr + 32) * GP + lc * 16) = pv1;
;         *(LAS u32x2*)(lds + G_A16 + ar * 32 + ac * 8) = pa;
;         __syncthreads();
.LBB0_403:
	s_add_i32 s28, s76, 1
	v_add_u32_e32 v171, v115, v116
	s_cmp_eq_u32 s76, 0
	s_cbranch_scc1 .Lg7_old
	s_waitcnt vmcnt(0)
	ds_write_b64 v155, v[126:127] offset:64512
	s_branch .Lg7_join

.LBB0_409:
	s_lshl_b32 s2, s25, 6
	s_add_u32 s77, s15, s2
	s_addc_u32 s25, s14, 0
	v_mov_b64_e32 v[34:35], s[88:89]
	s_mul_i32 vcc_lo, s25, 0x1c00
	s_mov_b32 s25, s9
	s_mov_b32 s85, s9
	v_or_b32_e32 v36, s77, v184
	v_mad_u64_u32 v[36:37], s[2:3], v36, s13, v[34:35]
	v_add_u32_e32 v37, vcc_lo, v37
	v_lshl_add_u64 v[70:71], v[36:37], 0, s[8:9]
	v_lshl_add_u64 v[76:77], v[36:37], 0, s[24:25]
	v_lshl_add_u64 v[76:77], v[76:77], 0, s[84:85]
	v_lshl_add_u64 v[70:71], v[70:71], 0, v[200:201]
	v_lshl_add_u64 v[76:77], v[76:77], 0, v[192:193]
	v_or_b32_e32 v36, s77, v185
	v_mad_u64_u32 v[36:37], s[2:3], v36, s13, v[34:35]
	v_add_u32_e32 v37, vcc_lo, v37
	v_lshl_add_u64 v[72:73], v[36:37], 0, s[8:9]
	v_lshl_add_u64 v[78:79], v[36:37], 0, s[24:25]
	v_lshl_add_u64 v[78:79], v[78:79], 0, s[84:85]
	v_lshl_add_u64 v[72:73], v[72:73], 0, v[248:249]
	v_lshl_add_u64 v[78:79], v[78:79], 0, v[194:195]
	v_or_b32_e32 v36, s77, v205
	v_mad_u64_u32 v[36:37], s[2:3], v36, s13, v[34:35]
	v_add_u32_e32 v37, vcc_lo, v37
	v_lshl_add_u64 v[74:75], v[36:37], 0, s[8:9]
	v_lshl_add_u64 v[80:81], v[36:37], 0, s[24:25]
	v_lshl_add_u64 v[80:81], v[80:81], 0, s[84:85]
	v_lshl_add_u64 v[74:75], v[74:75], 0, v[250:251]
	v_lshl_add_u64 v[80:81], v[80:81], 0, v[196:197]
	v_or_b32_e32 v34, s77, v120
	v_mad_u64_u32 v[34:35], s[2:3], v34, s13, v[122:123]
	v_add_u32_e32 v35, vcc_lo, v35
	global_load_dwordx2 v[126:127], v[34:35], off

; #define LAS __attribute__((address_space(3)))
; __device__ __forceinline__ bf16_t f2bf(float f) { return (bf16_t)(cvtpk(f, 0.f) & 0xffffu); }
; __device__ __forceinline__ int crow(int r, int hi) { return (r & 3) + 8 * (r >> 2) + 4 * hi; }
; __device__ __forceinline__ s16x4 trread(const LAS char* p) { return __builtin_bit_cast(s16x4, __builtin_amdgcn_ds_read_tr16_b64_v4i16((LAS s16x4*)p)); }
; __device__ __forceinline__ void gla_unit(LAS char* lds0, int b, int h, int dvh, bf16_t* Z, bf16_t* OT, const float* afw, const float* afb, const float* abw, const float* abb, bool dry) {
;     ...
; #pragma unroll
;             for (int k = 0; k < 4; ++k) {
;                 const bf16x8 a = *(const LAS bf16x8*)(lds + G_Q + (32 * I + r32) * GP + (16 * k + 8 * hi) * 2);
;                 const LAS char* sp = lds + G_SB + (16 * k + 8 * hi + q4) * GP + (32 * J + 16 * g16 + 4 * p4) * 2;
;                 const s16x4 l0 = trread(sp), l1 = trread(sp + 4 * GP);
;                 oacc = __builtin_amdgcn_mfma_f32_32x32x16_bf16(a, MK8(l0, l1), oacc, 0, 0, 0);
;             }
; #pragma unroll
;             for (int r = 0; r < 16; ++r) { const int i_ = 32 * I + crow(r, hi), j_ = 32 * J + r32;
;                 ((LAS bf16_t*)(lds + G_AM))[i_ * (GP / 2) + j_] = f2bf((i_ >= j_) ? Ac[r] : 0.f); }
;         }
;         asm volatile("s_waitcnt lgkmcnt(0)\n\ts_barrier" ::: "memory");
.LBB0_420:
	s_nop 9
	v_add_u32_e32 v173, v137, v154
	ds_read_b128 v[54:57], v239 offset:46080
	ds_read_b128 v[174:177], v239 offset:46112
	ds_read_b128 v[178:181], v239 offset:46144
	ds_read_b128 v[188:191], v239 offset:46176
	v_cndmask_b32_e64 v34, v34, 0, s[42:43]
	v_cndmask_b32_e64 v35, v35, 0, s[44:45]
	v_cndmask_b32_e64 v36, v36, 0, s[46:47]
	v_cndmask_b32_e64 v37, v37, 0, s[50:51]
	v_cvt_pk_bf16_f32 v242, v34, v35
	v_cvt_pk_bf16_f32 v243, v36, v37
	ds_write_b64 v238, v[242:243] offset:36864
	s_waitcnt lgkmcnt(4)
	v_mfma_f32_32x32x16_bf16 v[50:65], v[50:53], v[54:57], 0
	v_cndmask_b32_e64 v38, v38, 0, s[52:53]
	v_cndmask_b32_e64 v39, v39, 0, s[54:55]
	v_cndmask_b32_e64 v40, v40, 0, s[56:57]
	v_cndmask_b32_e64 v41, v41, 0, s[58:59]
	v_cvt_pk_bf16_f32 v242, v38, v39
	v_cvt_pk_bf16_f32 v243, v40, v41
	ds_write_b64 v238, v[242:243] offset:36880
	s_waitcnt lgkmcnt(4)
	v_mfma_f32_32x32x16_bf16 v[50:65], v[106:109], v[174:177], v[50:65]
	v_cndmask_b32_e64 v42, v42, 0, s[60:61]
	v_cndmask_b32_e64 v43, v43, 0, s[62:63]
	v_cndmask_b32_e64 v44, v44, 0, s[64:65]
	v_cndmask_b32_e64 v45, v45, 0, s[66:67]
	v_cvt_pk_bf16_f32 v242, v42, v43
	v_cvt_pk_bf16_f32 v243, v44, v45
	ds_write_b64 v238, v[242:243] offset:36896
	s_waitcnt lgkmcnt(4)
	v_mfma_f32_32x32x16_bf16 v[50:65], v[102:105], v[178:181], v[50:65]
	v_cndmask_b32_e64 v46, v46, 0, s[68:69]
	v_cndmask_b32_e64 v47, v47, 0, s[70:71]
	v_cndmask_b32_e64 v48, v48, 0, s[72:73]
	v_cndmask_b32_e64 v49, v49, 0, s[74:75]
	v_cvt_pk_bf16_f32 v242, v46, v47
	v_cvt_pk_bf16_f32 v243, v48, v49
	ds_write_b64 v238, v[242:243] offset:36912
	s_waitcnt lgkmcnt(4)
	v_mfma_f32_32x32x16_bf16 v[50:65], v[110:113], v[188:191], v[50:65]
	s_waitcnt lgkmcnt(0)
	s_barrier
	s_cmpk_eq_i32 s29, 0xffdd
	s_cbranch_scc1 .Lg7_nqk
	v_readfirstlane_b32 s96, v241
	s_mov_b32 m0, s96
	s_nop 0
	global_load_lds_dwordx4 v[70:71], off
	s_add_i32 s98, s96, 0x1000
	s_mov_b32 m0, s98
	s_nop 0
	global_load_lds_dwordx4 v[72:73], off
	v_lshl_add_u64 v[82:83], v[70:71], 0, v[198:199]
	v_lshl_add_u64 v[84:85], v[72:73], 0, v[198:199]
	s_add_i32 s98, s96, 0x2400
	s_mov_b32 m0, s98
	s_nop 0
	global_load_lds_dwordx4 v[82:83], off
	s_add_i32 s98, s96, 0x3400
	s_mov_b32 m0, s98
	s_nop 0
	global_load_lds_dwordx4 v[84:85], off
	s_cmp_lg_u32 s18, 0
	s_cbranch_scc1 .Lg7_nqk
	s_add_i32 s98, s96, 0x2000
	s_mov_b32 m0, s98
	s_nop 0
	global_load_lds_dwordx4 v[74:75], off
	v_lshl_add_u64 v[82:83], v[74:75], 0, v[198:199]
	s_add_i32 s98, s96, 0x4400
	s_mov_b32 m0, s98
	s_nop 0
	global_load_lds_dwordx4 v[82:83], off
; #define LAS __attribute__((address_space(3)))
; __device__ __forceinline__ void gla_unit(LAS char* lds0, int b, int h, int dvh, bf16_t* Z, bf16_t* OT, const float* afw, const float* afb, const float* abw, const float* abb, bool dry) {
;     ...
;             for (int u = 0; u < 4; ++u) {
;                 const bf16x8 a = *(const LAS bf16x8*)(lds + G_AM + (32 * I + r32) * GP + (16 * u + 8 * hi) * 2);
;                 const LAS char* vp = lds + G_V + (16 * u + 8 * hi + q4) * GP + (32 * J + 16 * g16 + 4 * p4) * 2;
;                 const s16x4 l0 = trread(vp), l1 = trread(vp + 4 * GP);
;                 oacc = __builtin_amdgcn_mfma_f32_32x32x16_bf16(a, MK8(l0, l1), oacc, 0, 0, 0);
;             }
; #pragma unroll
;             for (int r = 0; r < 16; ++r) ((LAS bf16_t*)(lds + G_O))[(32 * I + crow(r, hi)) * (GP / 2) + 32 * J + r32] = f2bf(oacc[r]);
;             const int Dd = I;
; #pragma unroll
;             for (int k = 0; k < 4; ++k) { const f32x4 dc = *(const LAS f32x4*)(lds + G_DEC + (32 * Dd + 8 * k + 4 * hi) * 4);
; #pragma unroll
;                 for (int j = 0; j < 4; ++j) S[4 * k + j] *= dc[j]; }
; #pragma unroll
;             for (int u = 0; u < 4; ++u) {
;                 const LAS char* kp = lds + G_KD + (16 * u + 8 * hi + q4) * GP + (32 * Dd + 16 * g16 + 4 * p4) * 2;
;                 const LAS char* vp = lds + G_V + (16 * u + 8 * hi + q4) * GP + (32 * J + 16 * g16 + 4 * p4) * 2;
;                 const s16x4 k0 = trread(kp), k1 = trread(kp + 4 * GP), v0 = trread(vp), v1 = trread(vp + 4 * GP);
;                 S = __builtin_amdgcn_mfma_f32_32x32x16_bf16(MK8(k0, k1), MK8(v0, v1), S, 0, 0, 0);
;             }
;         }
;         asm volatile("s_waitcnt lgkmcnt(0)\n\ts_barrier" ::: "memory");
; #pragma unroll
;         for (int r = 0; r < 16; ++r) ((LAS bf16_t*)(lds + G_SB))[(32 * I + crow(r, hi)) * (GP / 2) + 32 * J + r32] = f2bf(S[r]);
;         {
;             u32x4 o0v = *(const LAS u32x4*)(lds + G_O + lr * GP + lc * 16), o1v = *(const LAS u32x4*)(lds + G_O + (lr + 32) * GP + lc * 16);
;             if (second) {
;                 o0v.x = cvtpk(bflo(o0v.x) + bflo(prv0.x), bfhi(o0v.x) + bfhi(prv0.x)); o0v.y = cvtpk(bflo(o0v.y) + bflo(prv0.y), bfhi(o0v.y) + bfhi(prv0.y));
;                 o0v.z = cvtpk(bflo(o0v.z) + bflo(prv0.z), bfhi(o0v.z) + bfhi(prv0.z)); o0v.w = cvtpk(bflo(o0v.w) + bflo(prv0.w), bfhi(o0v.w) + bfhi(prv0.w));
.Lg7_nqk:
	ds_read_b64_tr_b16 v[34:35], v166 offset:36864
	ds_read_b64_tr_b16 v[36:37], v166 offset:37440
	ds_read_b64_tr_b16 v[38:39], v173 offset:27648
	ds_read_b64_tr_b16 v[40:41], v173 offset:28224
	ds_read_b64_tr_b16 v[42:43], v166 offset:39168
	ds_read_b64_tr_b16 v[44:45], v166 offset:39744
	ds_read_b64_tr_b16 v[46:47], v157 offset:27648
	ds_read_b64_tr_b16 v[48:49], v157 offset:28224
	s_andn2_b64 vcc, exec, s[2:3]
	s_mov_b64 s[2:3], -1
	s_waitcnt lgkmcnt(4)
	v_mfma_f32_32x32x16_bf16 v[50:65], v[34:37], v[38:41], v[50:65]
	ds_read_b64_tr_b16 v[34:35], v166 offset:41472
	ds_read_b64_tr_b16 v[36:37], v166 offset:42048
	ds_read_b64_tr_b16 v[38:39], v158 offset:27648
	ds_read_b64_tr_b16 v[40:41], v158 offset:28224
	s_waitcnt lgkmcnt(4)
	v_mfma_f32_32x32x16_bf16 v[50:65], v[42:45], v[46:49], v[50:65]
	ds_read_b64_tr_b16 v[42:43], v166 offset:43776
	ds_read_b64_tr_b16 v[44:45], v166 offset:44352
	ds_read_b64_tr_b16 v[46:47], v159 offset:27648
	ds_read_b64_tr_b16 v[48:49], v159 offset:28224
	s_waitcnt lgkmcnt(4)
	v_mfma_f32_32x32x16_bf16 v[50:65], v[34:37], v[38:41], v[50:65]
	s_waitcnt lgkmcnt(0)
	v_mfma_f32_32x32x16_bf16 v[50:65], v[42:45], v[46:49], v[50:65]
	s_nop 11
	v_cvt_pk_bf16_f32 v34, v50, s0
	ds_write_b16 v161, v34 offset:55296
	v_cvt_pk_bf16_f32 v34, v51, s0
	ds_write_b16 v161, v34 offset:55440
	v_cvt_pk_bf16_f32 v34, v52, s0
	ds_write_b16 v161, v34 offset:55584
	v_cvt_pk_bf16_f32 v34, v53, s0
	ds_write_b16 v161, v34 offset:55728
	v_cvt_pk_bf16_f32 v34, v54, s0
	ds_write_b16 v161, v34 offset:56448
	v_cvt_pk_bf16_f32 v34, v55, s0
	ds_write_b16 v161, v34 offset:56592
	v_cvt_pk_bf16_f32 v34, v56, s0
	ds_write_b16 v161, v34 offset:56736
	v_cvt_pk_bf16_f32 v34, v57, s0
	ds_write_b16 v161, v34 offset:56880
	v_cvt_pk_bf16_f32 v34, v58, s0
	ds_write_b16 v161, v34 offset:57600
	v_cvt_pk_bf16_f32 v34, v59, s0
	ds_write_b16 v161, v34 offset:57744
	v_cvt_pk_bf16_f32 v34, v60, s0
	ds_write_b16 v161, v34 offset:57888
	v_cvt_pk_bf16_f32 v34, v61, s0
	ds_write_b16 v161, v34 offset:58032
	v_cvt_pk_bf16_f32 v34, v62, s0
	ds_write_b16 v161, v34 offset:58752
	v_cvt_pk_bf16_f32 v34, v63, s0
	ds_write_b16 v161, v34 offset:58896
	v_cvt_pk_bf16_f32 v34, v64, s0
	ds_write_b16 v161, v34 offset:59040
	v_cvt_pk_bf16_f32 v34, v65, s0
	ds_write_b16 v161, v34 offset:59184
	ds_read_b128 v[34:37], v165
	ds_read_b128 v[38:41], v164
	ds_read_b128 v[42:45], v163
	ds_read_b128 v[46:49], v162
	s_waitcnt lgkmcnt(3)
	v_pk_mul_f32 v[30:31], v[30:31], v[34:35]
	s_waitcnt lgkmcnt(2)
	v_pk_mul_f32 v[26:27], v[26:27], v[38:39]
	s_waitcnt lgkmcnt(1)
	v_pk_mul_f32 v[22:23], v[22:23], v[42:43]
	s_waitcnt lgkmcnt(0)
	v_pk_mul_f32 v[18:19], v[18:19], v[46:47]
	v_pk_mul_f32 v[32:33], v[32:33], v[36:37]
	v_pk_mul_f32 v[28:29], v[28:29], v[40:41]
	v_pk_mul_f32 v[24:25], v[24:25], v[44:45]
	v_pk_mul_f32 v[20:21], v[20:21], v[48:49]
	ds_read_b128 v[34:37], v172 offset:18432
	ds_read_b64_tr_b16 v[38:39], v173 offset:27648
	ds_read_b64_tr_b16 v[40:41], v173 offset:28224
	ds_read_b128 v[42:45], v172 offset:18464
	ds_read_b64_tr_b16 v[46:47], v173 offset:29952
	ds_read_b64_tr_b16 v[48:49], v173 offset:30528
	ds_read_b64_tr_b16 v[50:51], v173 offset:32256
	ds_read_b64_tr_b16 v[56:57], v173 offset:35136
	s_waitcnt lgkmcnt(5)
	v_mfma_f32_32x32x16_bf16 v[18:33], v[34:37], v[38:41], v[18:33]
	ds_read_b128 v[34:37], v172 offset:18496
	ds_read_b64_tr_b16 v[52:53], v173 offset:32832
	ds_read_b64_tr_b16 v[54:55], v173 offset:34560
	ds_read_b128 v[38:41], v172 offset:18528
	s_waitcnt lgkmcnt(0)
	s_barrier
	s_cmpk_eq_i32 s29, 0xffdd
	s_cbranch_scc1 .Lg7_nv
	s_add_i32 s98, s96, 0x6c00
	s_mov_b32 m0, s98
	s_nop 0
	global_load_lds_dwordx4 v[76:77], off
	s_add_i32 s98, s96, 0x7c00
	s_mov_b32 m0, s98
	s_nop 0
	global_load_lds_dwordx4 v[78:79], off
	s_cmp_lg_u32 s18, 0
	s_cbranch_scc1 .Lg7_nv
	s_add_i32 s98, s96, 0x8c00
	s_mov_b32 m0, s98
	s_nop 0
	global_load_lds_dwordx4 v[80:81], off
.Lg7_nv:
	s_waitcnt lgkmcnt(8)
	v_mfma_f32_32x32x16_bf16 v[18:33], v[42:45], v[46:49], v[18:33]
	s_waitcnt lgkmcnt(3)
	v_mfma_f32_32x32x16_bf16 v[18:33], v[34:37], v[50:53], v[18:33]
	s_waitcnt lgkmcnt(0)
	v_mfma_f32_32x32x16_bf16 v[18:33], v[38:41], v[54:57], v[18:33]
	s_nop 11
	v_cvt_pk_bf16_f32 v242, v18, v19
	v_cvt_pk_bf16_f32 v243, v20, v21
	ds_write_b64 v238, v[242:243] offset:46080
	v_cvt_pk_bf16_f32 v242, v22, v23
	v_cvt_pk_bf16_f32 v243, v24, v25
	ds_write_b64 v238, v[242:243] offset:46096
	v_cvt_pk_bf16_f32 v242, v26, v27
	v_cvt_pk_bf16_f32 v243, v28, v29
	ds_write_b64 v238, v[242:243] offset:46112
	v_cvt_pk_bf16_f32 v242, v30, v31
	v_cvt_pk_bf16_f32 v243, v32, v33
	ds_write_b64 v238, v[242:243] offset:46128
	ds_read_b128 v[38:41], v171 offset:55296
	ds_read_b128 v[34:37], v167 offset:55296
	s_cbranch_vccnz .LBB0_422
	s_mov_b64 s[2:3], 0
.LBB0_422:
	s_andn2_b64 vcc, exec, s[2:3]
	s_cbranch_vccnz .LBB0_402
	s_waitcnt lgkmcnt(1)
	v_lshlrev_b32_e32 v42, 16, v38
	v_and_b32_e32 v43, 0xffff0000, v38
	s_cmpk_eq_i32 s29, 0xffdd
	s_cbranch_scc1 .Lg7_w1
	s_waitcnt vmcnt(7)
	s_branch .Lg7_w1d
.Lg7_w1:
	s_waitcnt vmcnt(1)
.Lg7_w1d:
	v_lshlrev_b32_e32 v44, 16, v98
	v_and_b32_e32 v45, 0xffff0000, v98
	v_pk_add_f32 v[42:43], v[44:45], v[42:43]
	v_lshlrev_b32_e32 v44, 16, v99
	v_cvt_pk_bf16_f32 v38, v42, v43
	v_lshlrev_b32_e32 v42, 16, v39
	v_and_b32_e32 v43, 0xffff0000, v39
	v_and_b32_e32 v45, 0xffff0000, v99
	v_pk_add_f32 v[42:43], v[44:45], v[42:43]
	v_lshlrev_b32_e32 v44, 16, v100
	v_cvt_pk_bf16_f32 v39, v42, v43
	v_lshlrev_b32_e32 v42, 16, v40
	v_and_b32_e32 v43, 0xffff0000, v40
	v_and_b32_e32 v45, 0xffff0000, v100
	v_pk_add_f32 v[42:43], v[44:45], v[42:43]
	v_lshlrev_b32_e32 v44, 16, v101
	v_cvt_pk_bf16_f32 v40, v42, v43
	v_lshlrev_b32_e32 v42, 16, v41
	v_and_b32_e32 v43, 0xffff0000, v41
	v_and_b32_e32 v45, 0xffff0000, v101
	v_pk_add_f32 v[42:43], v[44:45], v[42:43]
	s_cmpk_eq_i32 s29, 0xffdd
	s_cbranch_scc1 .Lg7_w0
	s_waitcnt vmcnt(6)
	s_branch .Lg7_w0d

; __device__ __forceinline__ unsigned cvtpk(float lo, float hi) { f32x2 v = {lo, hi}; bf16x2_t b = __builtin_convertvector(v, bf16x2_t); return __builtin_bit_cast(unsigned, b); }
; __device__ __forceinline__ float bflo(unsigned u) { return __uint_as_float(u << 16); }
; __device__ __forceinline__ float bfhi(unsigned u) { return __uint_as_float(u & 0xffff0000u); }
; __device__ __forceinline__ void gla_unit(LAS char* lds0, int b, int h, int dvh, bf16_t* Z, bf16_t* OT, const float* afw, const float* afb, const float* abw, const float* abb, bool dry) {
;     ...
;                 o0v.x = cvtpk(bflo(o0v.x) + bflo(prv0.x), bfhi(o0v.x) + bfhi(prv0.x)); o0v.y = cvtpk(bflo(o0v.y) + bflo(prv0.y), bfhi(o0v.y) + bfhi(prv0.y));
;                 o0v.z = cvtpk(bflo(o0v.z) + bflo(prv0.z), bfhi(o0v.z) + bfhi(prv0.z)); o0v.w = cvtpk(bflo(o0v.w) + bflo(prv0.w), bfhi(o0v.w) + bfhi(prv0.w));
;                 o1v.x = cvtpk(bflo(o1v.x) + bflo(prv1.x), bfhi(o1v.x) + bfhi(prv1.x)); o1v.y = cvtpk(bflo(o1v.y) + bflo(prv1.y), bfhi(o1v.y) + bfhi(prv1.y));
;                 o1v.z = cvtpk(bflo(o1v.z) + bflo(prv1.z), bfhi(o1v.z) + bfhi(prv1.z)); o1v.w = cvtpk(bflo(o1v.w) + bflo(prv1.w), bfhi(o1v.w) + bfhi(prv1.w));
;             }
;             if (!dry) { *(u32x4*)og0 = o0v; *(u32x4*)og1 = o1v; }
.Lg7_w0d:
	v_lshlrev_b32_e32 v44, 16, v94
	v_cvt_pk_bf16_f32 v41, v42, v43
	s_waitcnt lgkmcnt(0)
	v_lshlrev_b32_e32 v42, 16, v34
	v_and_b32_e32 v43, 0xffff0000, v34
	v_and_b32_e32 v45, 0xffff0000, v94
	v_pk_add_f32 v[42:43], v[44:45], v[42:43]
	v_lshlrev_b32_e32 v44, 16, v95
	v_cvt_pk_bf16_f32 v34, v42, v43
	v_lshlrev_b32_e32 v42, 16, v35
	v_and_b32_e32 v43, 0xffff0000, v35
	v_and_b32_e32 v45, 0xffff0000, v95
	v_pk_add_f32 v[42:43], v[44:45], v[42:43]
	v_lshlrev_b32_e32 v44, 16, v96
	v_cvt_pk_bf16_f32 v35, v42, v43
	v_lshlrev_b32_e32 v42, 16, v36
	v_and_b32_e32 v43, 0xffff0000, v36
	v_and_b32_e32 v45, 0xffff0000, v96
	v_pk_add_f32 v[42:43], v[44:45], v[42:43]
	v_lshlrev_b32_e32 v44, 16, v97
	v_cvt_pk_bf16_f32 v36, v42, v43
	v_lshlrev_b32_e32 v42, 16, v37
	v_and_b32_e32 v43, 0xffff0000, v37
	v_and_b32_e32 v45, 0xffff0000, v97
	v_pk_add_f32 v[42:43], v[44:45], v[42:43]
	s_nop 0
	v_cvt_pk_bf16_f32 v37, v42, v43
	s_branch .LBB0_402
